# baseline (speedup 1.0000x reference)
; #define tid fresh_tid(wid1)
; template <bool DIFF>
; __device__ __forceinline__ void attn_item(const Params& p, int l, int I, LAS unsigned char* lds, const int tid) {
;     ...
;     const int qrow = qrow0 + 32 * wid + r32;
;     bf16x8 qf[DIFF ? 4 : 6];
;     if (DIFF) {
;         const bf16_t* qp = DQb + (size_t)qrow * 512 + 64 * h + 8 * hi;
;         qf[0] = *(const bf16x8*)(qp); qf[1] = *(const bf16x8*)(qp + 16); qf[2] = *(const bf16x8*)(qp + 32); qf[3] = *(const bf16x8*)(qp + 48);
;     } else {
;         const bf16_t* qp = Qb + (size_t)qrow * 768 + 96 * h + 8 * hi;
; #pragma unroll
;         for (int d0 = 0; d0 < 6; ++d0) qf[d0] = *(const bf16x8*)(qp + 16 * d0);
;     }
;     const int rowk = tid >> 3, c8 = tid & 7;
;     const int rowq = (lane & 15) + 16 * (wid & 3), cq8 = (lane >> 4) + 4 * (wid >> 2);
;     const int rowr = (lane & 15) + 16 * wid, cr4 = lane >> 4;
;     const unsigned kw0 = cq8 * 1024 + rowq * 16, vw = AT_V + (c8 >> 2) * 4096 + rowk * 64 + (c8 & 3) * 16, kw2 = (8 + cr4) * 1024 + rowr * 16;
;     u32x4 g0[2], g1[2], g2[2];
;     auto keyrow = [&](int t) { return t < 4 ? ctxbase + 64 * t : latbase + 64 * (t - 4); };
;     auto gload = [&](int t, const int j) {
;         const int kr0 = keyrow(t);
;         if (DIFF) { g0[j] = *(const u32x4*)(DKb + (size_t)(kr0 + rowq) * 512 + 64 * h + 8 * cq8); g1[j] = *(const u32x4*)(DVb + (size_t)(kr0 + rowk) * 512 + 64 * h + 8 * c8); }
;         else { g0[j] = *(const u32x4*)(KVb + (size_t)(kr0 + rowq) * 1024 + 128 * h + 8 * cq8); g1[j] = *(const u32x4*)(KVb + (size_t)(kr0 + rowk) * 1024 + 128 * h + 64 + 8 * c8);
;             if (tid < 256) g2[j] = *(const u32x4*)(KRb + (size_t)(kr0 + rowr) * 32 + 8 * cr4); }
;     };
;     auto lwrite = [&](int slot, const int j) {
;         LAS unsigned char* sb = lds + slot * AT_SLOT + j * AT_SUB;
;         *(LAS u32x4*)(sb + kw0) = g0[j]; *(LAS u32x4*)(sb + vw) = g1[j];
;         if (!DIFF) { if (tid < 256) *(LAS u32x4*)(sb + kw2) = g2[j]; }
;     };
;     LAS float* scr = (LAS float*)(lds + AT_SCR + wid * 512);
;     float mref1 = 0.f, l1 = 0.f, mref2 = 0.f, l2 = 0.f;
;     f32x16 o1[2], o2[2];
;     float zf = 0.f; asm volatile("" : "+v"(zf));
; #pragma unroll
;     for (int r = 0; r < 16; ++r) { o1[0][r] = zf; o1[1][r] = zf; o2[0][r] = zf; o2[1][r] = zf; }
;     const float sc = (DIFF ? 0.17677669529663687f : 0.10206207261596575f) * LOG2E;
; #pragma unroll
.LBB0_491:
	s_and_b32 s4, s25, 0xffffe000
	s_sub_i32 s30, s4, 64
	s_mov_b32 s4, 0
	s_and_b32 s37, s26, 0xffffff00
	v_mbcnt_lo_u32_b32 v0, -1, s4
	v_mbcnt_hi_u32_b32 v169, -1, v0
	v_add_u32_e32 v4, s24, v169
	s_add_i32 s31, s37, 0x8000
	v_readfirstlane_b32 s4, v4
	s_ashr_i32 s29, s4, 6
	s_lshl_b32 s4, s26, 5
	s_and_b32 s36, s4, 0xffffe000
	s_and_b32 s18, s4, 0xffffff00
	s_mov_b32 s4, 30
	s_mov_b32 s4, 30
	s_mov_b32 s4, 30
	s_mov_b32 s4, 30
	s_ashr_i32 s5, s4, 31
	s_lshl_b64 s[4:5], s[4:5], 3
	s_add_u32 s4, s0, s4
	s_addc_u32 s5, s1, s5
	s_load_dwordx2 s[4:5], s[4:5], 0x0
	s_mov_b32 s8, 30
	v_and_b32_e32 v170, 31, v169
	v_bfe_u32 v171, v169, 5, 1
	v_lshlrev_b32_e32 v192, 4, v171
	s_waitcnt lgkmcnt(0)
	s_add_u32 s6, s4, 0x4000000
	s_mov_b32 s4, 30
	s_addc_u32 s7, s5, 0
	s_ashr_i32 s5, s4, 31
	s_lshl_b64 s[4:5], s[4:5], 3
	s_add_u32 s4, s0, s4
	s_addc_u32 s5, s1, s5
	s_load_dwordx2 s[4:5], s[4:5], 0x0
	s_ashr_i32 s9, s8, 31
	s_lshl_b64 s[8:9], s[8:9], 3
	s_add_u32 s8, s0, s8
	s_addc_u32 s9, s1, s9
	s_lshl_b32 s27, s29, 5
	s_add_i32 s27, s27, s18
	v_or_b32_e32 v0, s27, v170
	v_ashrrev_i32_e32 v1, 31, v0
	s_lshl_b32 s18, s26, 6
	v_lshlrev_b64 v[0:1], 10, v[0:1]
	s_and_b32 s28, s18, 0x1c0
	v_lshl_add_u64 v[0:1], s[6:7], 0, v[0:1]
	s_lshl_b32 s78, s28, 1
	v_lshl_add_u64 v[0:1], v[0:1], 0, s[78:79]
	s_mov_b32 s19, 30
	v_lshl_add_u64 v[2:3], v[0:1], 0, v[192:193]
	s_load_dwordx2 s[8:9], s[8:9], 0x0
	global_load_dwordx4 v[16:19], v[2:3], off
	global_load_dwordx4 v[20:23], v[2:3], off offset:32
	global_load_dwordx4 v[24:27], v[2:3], off offset:64
	global_load_dwordx4 v[28:31], v[2:3], off offset:96
	s_lshl_b32 s18, s29, 4
	s_lshl_b32 s19, s29, 9
	v_ashrrev_i32_e32 v172, 3, v4
	s_waitcnt lgkmcnt(0)
	s_add_u32 s4, s4, 0x11050000
	v_bfe_u32 v5, v169, 4, 2
	v_lshlrev_b32_e32 v6, 10, v169
	v_add_u32_e32 v4, s31, v172
	s_addc_u32 s5, s5, 0
	v_and_b32_e32 v41, 0x1000, v6
	v_and_or_b32 v6, s29, -4, v5
	v_ashrrev_i32_e32 v5, 31, v4
	s_add_u32 s8, s8, 0x13150000
	v_lshlrev_b64 v[32:33], 10, v[4:5]
	s_addc_u32 s9, s9, 0
	v_and_b32_e32 v37, 7, v169
	v_lshl_add_u64 v[32:33], s[8:9], 0, v[32:33]
	v_and_b32_e32 v1, 15, v169
	v_lshl_add_u64 v[32:33], v[32:33], 0, s[78:79]
	v_lshlrev_b32_e32 v38, 4, v37
	v_mov_b32_e32 v39, v193
	v_mov_b32_e32 v0, v193
	v_and_or_b32 v173, s18, 48, v1
	v_lshl_add_u64 v[32:33], v[32:33], 0, v[38:39]
	s_add_i32 s18, s37, 0x8040
	global_load_dwordx4 v[100:103], v[32:33], off
	v_or_b32_e32 v32, s18, v173
	v_ashrrev_i32_e32 v33, 31, v32
	v_lshlrev_b32_e32 v42, 10, v6
	v_lshlrev_b32_e32 v6, 3, v6
	v_lshlrev_b64 v[32:33], 10, v[32:33]
	v_ashrrev_i32_e32 v7, 31, v6
	v_lshl_add_u64 v[32:33], s[4:5], 0, v[32:33]
	v_lshlrev_b64 v[34:35], 1, v[6:7]
	v_or_b32_e32 v4, s31, v173
	v_lshl_add_u64 v[32:33], v[32:33], 0, s[78:79]
	v_ashrrev_i32_e32 v5, 31, v4
	v_lshl_add_u64 v[32:33], v[32:33], 0, v[34:35]
	v_lshlrev_b64 v[4:5], 10, v[4:5]
	global_load_dwordx4 v[108:111], v[32:33], off
	v_add_u32_e32 v32, s18, v172
	v_lshl_add_u64 v[4:5], s[4:5], 0, v[4:5]
	v_ashrrev_i32_e32 v33, 31, v32
	v_lshl_add_u64 v[4:5], v[4:5], 0, s[78:79]
	v_lshlrev_b64 v[32:33], 10, v[32:33]
	v_lshl_add_u64 v[4:5], v[4:5], 0, v[34:35]
	v_lshl_add_u64 v[32:33], s[8:9], 0, v[32:33]
	global_load_dwordx4 v[96:99], v[4:5], off
	v_lshl_add_u64 v[32:33], v[32:33], 0, s[78:79]
	v_lshl_add_u64 v[32:33], v[32:33], 0, v[38:39]
	global_load_dwordx4 v[116:119], v[32:33], off
	s_add_i32 s35, s19, 0
	s_add_i32 s35, s35, 0x14000
	s_add_u32 s4, s4, s78
	v_lshlrev_b32_e32 v40, 4, v169
	s_addc_u32 s5, s5, 0
	v_lshl_or_b32 v174, v173, 4, v42
	v_lshl_add_u64 v[164:165], s[4:5], 0, v[34:35]
	s_add_u32 s4, s8, s78
	v_mov_b32_e32 v14, v0
	v_mov_b32_e32 v15, v0
	s_addc_u32 s5, s9, 0
	v_and_b32_e32 v168, 63, v169
	v_mov_b32_e32 v1, v0
	v_mov_b32_e32 v2, v0
	v_mov_b32_e32 v3, v0
	v_mov_b32_e32 v4, v0
	v_mov_b32_e32 v5, v0
	v_mov_b32_e32 v6, v0
	v_mov_b32_e32 v7, v0
	v_mov_b32_e32 v8, v0
	v_mov_b32_e32 v9, v0
	v_mov_b32_e32 v10, v0
	v_mov_b32_e32 v11, v0
	v_mov_b32_e32 v12, v0
	v_mov_b32_e32 v13, v0
	s_waitcnt vmcnt(7)
	v_lshlrev_b32_e32 v36, 16, v16
	v_and_b32_e32 v37, 0xffff0000, v16
	v_lshlrev_b32_e32 v16, 16, v17
	v_and_b32_e32 v17, 0xffff0000, v17
	v_pk_mul_f32 v[16:17], v[16:17], s[74:75] op_sel_hi:[1,0]
	v_pk_mul_f32 v[32:33], v[36:37], s[74:75] op_sel_hi:[1,0]
	v_cvt_pk_bf16_f32 v105, v16, v17
	v_lshlrev_b32_e32 v16, 16, v18
	v_and_b32_e32 v17, 0xffff0000, v18
	v_pk_mul_f32 v[16:17], v[16:17], s[74:75] op_sel_hi:[1,0]
	v_cvt_pk_bf16_f32 v104, v32, v33
	v_cvt_pk_bf16_f32 v106, v16, v17
	v_lshlrev_b32_e32 v16, 16, v19
	v_and_b32_e32 v17, 0xffff0000, v19
	v_pk_mul_f32 v[16:17], v[16:17], s[74:75] op_sel_hi:[1,0]
	v_and_b32_e32 v178, 0xc0, v40
	v_cvt_pk_bf16_f32 v107, v16, v17
	s_waitcnt vmcnt(6)
	v_lshlrev_b32_e32 v16, 16, v20
	v_and_b32_e32 v17, 0xffff0000, v20
	v_pk_mul_f32 v[16:17], v[16:17], s[74:75] op_sel_hi:[1,0]
	v_lshl_add_u64 v[166:167], s[4:5], 0, v[38:39]
	v_cvt_pk_bf16_f32 v112, v16, v17
	v_lshlrev_b32_e32 v16, 16, v21
	v_and_b32_e32 v17, 0xffff0000, v21
	v_pk_mul_f32 v[16:17], v[16:17], s[74:75] op_sel_hi:[1,0]
	v_mov_b64_e32 v[62:63], v[14:15]
	v_cvt_pk_bf16_f32 v113, v16, v17
	v_lshlrev_b32_e32 v16, 16, v22
	v_and_b32_e32 v17, 0xffff0000, v22
	v_pk_mul_f32 v[16:17], v[16:17], s[74:75] op_sel_hi:[1,0]
	s_mov_b32 s34, 0
	v_cvt_pk_bf16_f32 v114, v16, v17
	v_lshlrev_b32_e32 v16, 16, v23
	v_and_b32_e32 v17, 0xffff0000, v23
	v_pk_mul_f32 v[16:17], v[16:17], s[74:75] op_sel_hi:[1,0]
	v_lshlrev_b32_e32 v177, 8, v171
	v_cvt_pk_bf16_f32 v115, v16, v17
	s_waitcnt vmcnt(5)
; #define LAS __attribute__((address_space(3)))
; __device__ __forceinline__ s16x4 vtr(const LAS unsigned char* p) { return __builtin_bit_cast(s16x4, __builtin_amdgcn_ds_read_tr16_b64_v4i16((LAS s16x4*)p)); }
; template <bool DIFF>
; __device__ __forceinline__ void attn_item(const Params& p, int l, int I, LAS unsigned char* lds, const int tid) {
;     ...
;     for (int r = 0; r < 16; ++r) { negm1[r] = zf; negm2[r] = zf; }
;     const unsigned vlane = ((lane >> 4) & 1) * 32 + (lane & 3) * 8 + (4 * hi + ((lane & 15) >> 2)) * 64;
;     gload(0, 0); gload(1, 1); lwrite(0, 0); lwrite(0, 1);
;     __syncthreads();
;     for (int st = 0; st < nt / 2; ++st) {
;         const bool more = (2 * st + 2 < nt);
;         if (more) { gload(2 * st + 2, 0); gload(2 * st + 3, 1); }
;     ...
;         const LAS unsigned char* sb = lds + (st & 1) * AT_SLOT + sub * AT_SUB;
;         const LAS unsigned char* kb = sb + hi * 1024 + r32 * 16;
;         const LAS unsigned char* vb = sb + AT_V + vlane;
;         bf16x8 vf[2][4];
; #pragma unroll
;         for (int dh = 0; dh < 2; ++dh)
; #pragma unroll
;             for (int k = 0; k < 4; ++k) { const s16x4 lo = vtr(vb + dh * 4096 + k * 1024), hh = vtr(vb + dh * 4096 + k * 1024 + 512);
;                 vf[dh][k] = (bf16x8){lo[0], lo[1], lo[2], lo[3], hh[0], hh[1], hh[2], hh[3]}; }
;         bf16x8 kf[NQ][2];
; #pragma unroll
;         for (int d0 = 0; d0 < NQ; ++d0) { kf[d0][0] = *(const LAS bf16x8*)(kb + d0 * 2048); kf[d0][1] = *(const LAS bf16x8*)(kb + d0 * 2048 + 512); }
	v_lshlrev_b32_e32 v16, 16, v24
	v_and_b32_e32 v17, 0xffff0000, v24
	v_pk_mul_f32 v[16:17], v[16:17], s[74:75] op_sel_hi:[1,0]
	v_lshlrev_b32_e32 v181, 10, v171
	v_cvt_pk_bf16_f32 v120, v16, v17
	v_lshlrev_b32_e32 v16, 16, v25
	v_and_b32_e32 v17, 0xffff0000, v25
	v_pk_mul_f32 v[16:17], v[16:17], s[74:75] op_sel_hi:[1,0]
	v_lshlrev_b32_e32 v182, 4, v170
	v_cvt_pk_bf16_f32 v121, v16, v17
	v_lshlrev_b32_e32 v16, 16, v26
	v_and_b32_e32 v17, 0xffff0000, v26
	v_pk_mul_f32 v[16:17], v[16:17], s[74:75] op_sel_hi:[1,0]
	v_cmp_gt_u32_e64 s[4:5], 32, v168
	v_cvt_pk_bf16_f32 v122, v16, v17
	v_lshlrev_b32_e32 v16, 16, v27
	v_and_b32_e32 v17, 0xffff0000, v27
	v_pk_mul_f32 v[16:17], v[16:17], s[74:75] op_sel_hi:[1,0]
	v_lshl_add_u32 v180, v170, 2, s35
	v_cvt_pk_bf16_f32 v123, v16, v17
	s_waitcnt vmcnt(4)
	v_lshlrev_b32_e32 v16, 16, v28
	v_and_b32_e32 v17, 0xffff0000, v28
	v_pk_mul_f32 v[16:17], v[16:17], s[74:75] op_sel_hi:[1,0]
	s_addk_i32 s36, 0xff00
	v_cvt_pk_bf16_f32 v124, v16, v17
	v_lshlrev_b32_e32 v16, 16, v29
	v_and_b32_e32 v17, 0xffff0000, v29
	v_pk_mul_f32 v[16:17], v[16:17], s[74:75] op_sel_hi:[1,0]
	s_add_i32 s37, s37, 0x80c0
	v_cvt_pk_bf16_f32 v125, v16, v17
	v_lshlrev_b32_e32 v16, 16, v30
	v_and_b32_e32 v17, 0xffff0000, v30
	v_pk_mul_f32 v[16:17], v[16:17], s[74:75] op_sel_hi:[1,0]
	v_add_u32_e32 v183, 0x80, v172
	v_cvt_pk_bf16_f32 v126, v16, v17
	v_lshlrev_b32_e32 v16, 16, v31
	v_and_b32_e32 v17, 0xffff0000, v31
	v_pk_mul_f32 v[16:17], v[16:17], s[74:75] op_sel_hi:[1,0]
	v_or_b32_e32 v184, 0x80, v173
	v_cvt_pk_bf16_f32 v127, v16, v17
	v_lshlrev_b32_e32 v16, 1, v169
	v_lshl_add_u32 v17, v172, 6, v41
	v_and_b32_e32 v175, 32, v16
	v_lshlrev_b32_e32 v16, 3, v169
	v_and_or_b32 v179, v40, 48, v17
	v_and_b32_e32 v176, 24, v16
	v_add_u32_e32 v16, 0, v174
	v_add_u32_e32 v17, 0, v179
	s_waitcnt vmcnt(1)
	ds_write_b128 v16, v[96:99]
	ds_write_b128 v17, v[100:103] offset:12288
	ds_write_b128 v16, v[108:111] offset:20480
	s_waitcnt vmcnt(0)
	ds_write_b128 v17, v[116:119] offset:32768
	v_mov_b64_e32 v[30:31], v[14:15]
	v_mov_b64_e32 v[46:47], v[14:15]
	v_mov_b32_e32 v161, 0
	v_mov_b64_e32 v[28:29], v[12:13]
	v_mov_b64_e32 v[26:27], v[10:11]
	v_mov_b64_e32 v[24:25], v[8:9]
	v_mov_b64_e32 v[22:23], v[6:7]
	v_mov_b64_e32 v[20:21], v[4:5]
	v_mov_b64_e32 v[18:19], v[2:3]
	v_mov_b64_e32 v[16:17], v[0:1]
	v_mov_b64_e32 v[44:45], v[12:13]
	v_mov_b64_e32 v[42:43], v[10:11]
	v_mov_b64_e32 v[40:41], v[8:9]
	v_mov_b64_e32 v[38:39], v[6:7]
	v_mov_b64_e32 v[36:37], v[4:5]
	v_mov_b64_e32 v[34:35], v[2:3]
	v_mov_b64_e32 v[32:33], v[0:1]
	v_mov_b64_e32 v[60:61], v[12:13]
	v_mov_b64_e32 v[58:59], v[10:11]
	v_mov_b64_e32 v[56:57], v[8:9]
	v_mov_b64_e32 v[54:55], v[6:7]
	v_mov_b64_e32 v[52:53], v[4:5]
	v_mov_b64_e32 v[50:51], v[2:3]
	v_mov_b64_e32 v[48:49], v[0:1]
	v_add_u32_e32 v181, v181, v182
	v_add3_u32 v175, v175, v176, v177
	v_add_u32_e32 v175, v175, v178
	v_lshlrev_b32_e32 v176, 10, v173
	v_mov_b32_e32 v177, 0
	v_lshl_add_u64 v[176:177], v[164:165], 0, v[176:177]
	v_lshlrev_b32_e32 v182, 10, v172
	v_mov_b32_e32 v183, 0
	v_lshl_add_u64 v[182:183], v[166:167], 0, v[182:183]
	v_mov_b32_e32 v194, 0
	v_mov_b32_e32 v195, 0
	v_mov_b32_e32 v196, 0
	v_mov_b32_e32 v197, 0
	v_mov_b32_e32 v198, 0
	v_mov_b32_e32 v199, 0
	v_mov_b32_e32 v200, 0
	v_mov_b32_e32 v201, 0
	v_mov_b32_e32 v202, 0
	v_mov_b32_e32 v203, 0
	v_mov_b32_e32 v204, 0
	v_mov_b32_e32 v205, 0
	v_mov_b32_e32 v206, 0
	v_mov_b32_e32 v207, 0
	v_mov_b32_e32 v208, 0
	v_mov_b32_e32 v209, 0
	v_mov_b32_e32 v218, 0
	v_mov_b32_e32 v219, 0
	v_mov_b32_e32 v220, 0
	v_mov_b32_e32 v221, 0
	v_mov_b32_e32 v222, 0
	v_mov_b32_e32 v223, 0
	v_mov_b32_e32 v224, 0
	v_mov_b32_e32 v225, 0
	v_mov_b32_e32 v226, 0
	v_mov_b32_e32 v227, 0
	v_mov_b32_e32 v228, 0
	v_mov_b32_e32 v229, 0
	v_mov_b32_e32 v230, 0
	v_mov_b32_e32 v231, 0
	v_mov_b32_e32 v232, 0
	v_mov_b32_e32 v233, 0
	v_mov_b32_e32 v185, 0
	v_mov_b32_e32 v162, 0
	v_mov_b32_e32 v186, 0
	s_waitcnt lgkmcnt(0)
	s_barrier
	s_branch .LBB0_493
.LBB0_492:
	s_add_i32 s34, s34, 1
	s_addk_i32 s30, 0x80
	s_cmpk_eq_i32 s34, 0x42
	s_waitcnt lgkmcnt(0)
	s_barrier
	s_cbranch_scc1 .LBB0_525
.LBB0_493:
	s_cmpk_lt_u32 s34, 0x41
	s_cselect_b64 s[8:9], -1, 0
	s_cmp_gt_u32 s34, 64
	s_cbranch_scc1 .LBB0_495
	s_cmp_eq_u32 s34, 0
	s_cselect_b32 s18, s31, s36
	s_cselect_b32 s20, s37, s30
	s_lshl_b32 s19, s34, 7
	s_add_i32 s18, s18, s19
	s_addk_i32 s18, 0x80
	s_lshl_b32 s18, s18, 10
	s_lshl_b32 s20, s20, 10
	s_mov_b32 s19, 0
	s_mov_b32 s21, 0
	v_lshl_add_u64 v[64:65], v[176:177], 0, s[18:19]
	global_load_dwordx4 v[96:99], v[64:65], off
	v_lshl_add_u64 v[64:65], v[182:183], 0, s[18:19]
	global_load_dwordx4 v[100:103], v[64:65], off
	v_lshl_add_u64 v[64:65], v[176:177], 0, s[20:21]
	global_load_dwordx4 v[108:111], v[64:65], off
	v_lshl_add_u64 v[64:65], v[182:183], 0, s[20:21]
	global_load_dwordx4 v[116:119], v[64:65], off
.LBB0_495:
	s_bitcmp1_b32 s34, 0
	s_cselect_b32 s18, 0xa000, 0
	v_add_u32_e32 v187, s18, v181
	v_add_u32_e32 v163, s18, v175
	ds_read_b128 v[234:237], v187
	ds_read_b128 v[238:241], v187 offset:512
	ds_read_b128 v[242:245], v187 offset:2048
	ds_read_b128 v[188:191], v187 offset:2560
	s_waitcnt lgkmcnt(0)
	v_mfma_f32_32x32x16_bf16 v[80:95], v[234:237], v[104:107], v[194:209]
	v_mfma_f32_32x32x16_bf16 v[80:95], v[242:245], v[112:115], v[80:95]
	v_mfma_f32_32x32x16_bf16 v[64:79], v[238:241], v[104:107], v[194:209]
	v_mfma_f32_32x32x16_bf16 v[64:79], v[188:191], v[112:115], v[64:79]
	ds_read_b64_tr_b16 v[128:129], v163 offset:12288
	ds_read_b64_tr_b16 v[130:131], v163 offset:12800
	ds_read_b64_tr_b16 v[144:145], v163 offset:16384
	ds_read_b64_tr_b16 v[146:147], v163 offset:16896
	ds_read_b64_tr_b16 v[132:133], v163 offset:13312
	ds_read_b64_tr_b16 v[134:135], v163 offset:13824
	ds_read_b64_tr_b16 v[148:149], v163 offset:17408
	ds_read_b64_tr_b16 v[150:151], v163 offset:17920
	ds_read_b128 v[234:237], v187 offset:4096
	ds_read_b128 v[238:241], v187 offset:4608
	ds_read_b128 v[242:245], v187 offset:6144
	ds_read_b128 v[188:191], v187 offset:6656
	s_waitcnt lgkmcnt(7)
	ds_read_b64_tr_b16 v[136:137], v163 offset:14336
	ds_read_b64_tr_b16 v[138:139], v163 offset:14848
	ds_read_b64_tr_b16 v[152:153], v163 offset:18432
	ds_read_b64_tr_b16 v[154:155], v163 offset:18944
	ds_read_b64_tr_b16 v[140:141], v163 offset:15360
	ds_read_b64_tr_b16 v[142:143], v163 offset:15872
	ds_read_b64_tr_b16 v[156:157], v163 offset:19456
	ds_read_b64_tr_b16 v[158:159], v163 offset:19968
	s_cmp_eq_u32 s34, 0
	s_cbranch_scc1 .Ldr_first_00
